# diff attn: next-tile LDS-DMA staging issued inside the tile bodies (between MFMAs) instead of at the tile header; producer publish skips L2 write-back in XCD-local mode
# speedup vs baseline: 1.1073x; 1.0083x over previous
.Ldiff_mask0:
	s_lshl_b32 s1, s0, 16
	v_add3_u32 v14, s1, v215, v216
	v_add3_u32 v15, s1, v195, v224
	s_sub_i32 s0, s35, 0x7f
	v_sub_u32_e32 v218, v193, v194
	v_subrev_u32_e32 v218, s0, v218
	s_xor_b32 s1, s1, 0x10000
	s_add_i32 s1, s41, s1
	ds_read_b128 v[2:5], v14
	v_xor_b32_e32 v217, 32, v14
	ds_read_b128 v[6:9], v217
	s_waitcnt lgkmcnt(1)
	v_mfma_f32_32x32x16_bf16 v[144:159], v[2:5], v[160:163], 0
	v_xor_b32_e32 v222, 64, v14
	ds_read_b128 v[10:13], v222
	s_waitcnt lgkmcnt(1)
	v_mfma_f32_32x32x16_bf16 v[144:159], v[6:9], v[164:167], v[144:159]
	v_xor_b32_e32 v223, 0x60, v14
	ds_read_b128 v[2:5], v223
	s_waitcnt lgkmcnt(1)
	v_mfma_f32_32x32x16_bf16 v[144:159], v[10:13], v[168:171], v[144:159]
	v_xor_b32_e32 v225, 0x80, v14
	ds_read_b128 v[6:9], v225
	s_waitcnt lgkmcnt(1)
	v_mfma_f32_32x32x16_bf16 v[144:159], v[2:5], v[172:175], v[144:159]
	v_xor_b32_e32 v230, 0xa0, v14
	ds_read_b128 v[10:13], v230
	s_waitcnt lgkmcnt(1)
	v_mfma_f32_32x32x16_bf16 v[236:251], v[6:9], v[176:179], 0
	v_xor_b32_e32 v231, 0xc0, v14
	ds_read_b128 v[2:5], v231
	s_mov_b32 m0, s1
	s_nop 0
	global_load_lds_dwordx4 v206, s[74:75]
	s_waitcnt lgkmcnt(1)
	v_mfma_f32_32x32x16_bf16 v[236:251], v[10:13], v[180:183], v[236:251]
	v_xor_b32_e32 v235, 0xe0, v14
	ds_read_b128 v[6:9], v235
	v_cmp_ge_i32_e64 s[4:5], v218, 0
	v_cmp_ge_i32_e64 s[6:7], v218, 1
	v_cmp_ge_i32_e64 s[10:11], v218, 2
	v_cmp_ge_i32_e64 s[20:21], v218, 3
	v_cmp_ge_i32_e64 s[46:47], v218, 4
	v_cmp_ge_i32_e64 s[48:49], v218, 5
	v_cmp_ge_i32_e64 s[50:51], v218, 6
	v_cmp_ge_i32_e64 s[76:77], v218, 7
	s_waitcnt lgkmcnt(1)
	v_mfma_f32_32x32x16_bf16 v[236:251], v[2:5], v[184:187], v[236:251]
	ds_read_b128 v[10:13], v15 offset:32768
	v_cmp_ge_i32_e64 s[84:85], v218, 16
	v_cmp_ge_i32_e64 s[86:87], v218, 17
	v_cmp_ge_i32_e64 s[88:89], v218, 18
	v_cmp_ge_i32_e64 s[90:91], v218, 19
	s_waitcnt lgkmcnt(1)
	v_mfma_f32_32x32x16_bf16 v[236:251], v[6:9], v[188:191], v[236:251]
	ds_read_b128 v[2:5], v15 offset:40960
	v_cmp_ge_i32_e64 s[92:93], v218, 20
	v_cmp_ge_i32_e64 s[94:95], v218, 21
	v_cmp_ge_i32_e64 s[96:97], v218, 22
	v_cmp_ge_i32_e64 vcc, v218, 23
	v_exp_f32_e32 v144, v144
	v_exp_f32_e32 v145, v145
	v_cndmask_b32_e64 v144, 0, v144, s[4:5]
	v_exp_f32_e32 v146, v146
	v_cndmask_b32_e64 v145, 0, v145, s[6:7]
	v_exp_f32_e32 v147, v147
	v_cndmask_b32_e64 v146, 0, v146, s[10:11]
	v_add_f32_e32 v0, v144, v145
	v_cvt_pk_bf16_f32 v144, v144, v145
	v_exp_f32_e32 v148, v148
	v_cndmask_b32_e64 v147, 0, v147, s[20:21]
	v_add_f32_e32 v0, v146, v0
	v_exp_f32_e32 v149, v149
	v_cndmask_b32_e64 v148, 0, v148, s[46:47]
	v_add_f32_e32 v0, v147, v0
	v_cvt_pk_bf16_f32 v145, v146, v147
	v_exp_f32_e32 v150, v150
	v_cndmask_b32_e64 v149, 0, v149, s[48:49]
	v_add_f32_e32 v0, v148, v0
	v_exp_f32_e32 v151, v151
	v_cndmask_b32_e64 v150, 0, v150, s[50:51]
	v_add_f32_e32 v0, v149, v0
	v_cvt_pk_bf16_f32 v146, v148, v149
	v_exp_f32_e32 v152, v152
	v_cndmask_b32_e64 v151, 0, v151, s[76:77]
	v_add_f32_e32 v0, v150, v0
	v_exp_f32_e32 v153, v153
	v_cndmask_b32_e64 v152, 0, v152, s[84:85]
	v_add_f32_e32 v0, v151, v0
	v_cvt_pk_bf16_f32 v147, v150, v151
	s_waitcnt lgkmcnt(1)
	s_nop 0
	v_mfma_f32_32x32x16_bf16 v[128:143], v[10:13], v[144:147], v[128:143]
	ds_read_b128 v[6:9], v15 offset:49152
	v_exp_f32_e32 v154, v154
	v_cndmask_b32_e64 v153, 0, v153, s[86:87]
	v_add_f32_e32 v0, v152, v0
	v_exp_f32_e32 v155, v155
	s_waitcnt lgkmcnt(1)
	v_mfma_f32_32x32x16_bf16 v[112:127], v[2:5], v[144:147], v[112:127]
	ds_read_b128 v[10:13], v15 offset:57344
	v_cndmask_b32_e64 v154, 0, v154, s[88:89]
	v_add_f32_e32 v0, v153, v0
	v_cvt_pk_bf16_f32 v148, v152, v153
	v_exp_f32_e32 v156, v156
	s_waitcnt lgkmcnt(1)
	v_mfma_f32_32x32x16_bf16 v[96:111], v[6:9], v[144:147], v[96:111]
	v_xor_b32_e32 v252, 32, v15
	ds_read_b128 v[2:5], v252 offset:32768
	v_cndmask_b32_e64 v155, 0, v155, s[90:91]
	v_add_f32_e32 v0, v154, v0
	v_exp_f32_e32 v157, v157
	v_cndmask_b32_e64 v156, 0, v156, s[92:93]
	s_waitcnt lgkmcnt(1)
	v_mfma_f32_32x32x16_bf16 v[80:95], v[10:13], v[144:147], v[80:95]
	ds_read_b128 v[6:9], v252 offset:40960
	v_add_f32_e32 v0, v155, v0
	v_cvt_pk_bf16_f32 v149, v154, v155
	v_exp_f32_e32 v158, v158
	v_cndmask_b32_e64 v157, 0, v157, s[94:95]
	v_add_f32_e32 v0, v156, v0
	v_exp_f32_e32 v159, v159
	v_cndmask_b32_e64 v158, 0, v158, s[96:97]
	v_add_f32_e32 v0, v157, v0
	v_cvt_pk_bf16_f32 v150, v156, v157
	v_cndmask_b32_e64 v159, 0, v159, vcc
	v_add_f32_e32 v0, v158, v0
	v_add_f32_e32 v0, v159, v0
	v_cvt_pk_bf16_f32 v151, v158, v159
	s_waitcnt lgkmcnt(1)
	s_nop 0
	v_mfma_f32_32x32x16_bf16 v[128:143], v[2:5], v[148:151], v[128:143]
	ds_read_b128 v[10:13], v252 offset:49152
	s_add_i32 m0, s1, 0x8000
	s_nop 0
	global_load_lds_dwordx4 v198, s[74:75]
	v_add_f32_e32 v197, v197, v0
	v_exp_f32_e32 v236, v236
	v_exp_f32_e32 v237, v237
	v_cndmask_b32_e64 v236, 0, v236, s[4:5]
	s_waitcnt lgkmcnt(1)
	v_mfma_f32_32x32x16_bf16 v[112:127], v[6:9], v[148:151], v[112:127]
	ds_read_b128 v[2:5], v252 offset:57344
	v_exp_f32_e32 v238, v238
	v_cndmask_b32_e64 v237, 0, v237, s[6:7]
	v_exp_f32_e32 v239, v239
	v_cndmask_b32_e64 v238, 0, v238, s[10:11]
	s_waitcnt lgkmcnt(1)
	v_mfma_f32_32x32x16_bf16 v[96:111], v[10:13], v[148:151], v[96:111]
	ds_read_b128 v[6:9], v14 offset:8192
	v_add_f32_e32 v0, v236, v237
	v_cvt_pk_bf16_f32 v236, v236, v237
	v_exp_f32_e32 v240, v240
	v_cndmask_b32_e64 v239, 0, v239, s[20:21]
	s_waitcnt lgkmcnt(1)
	v_mfma_f32_32x32x16_bf16 v[80:95], v[2:5], v[148:151], v[80:95]
	ds_read_b128 v[10:13], v217 offset:8192
	v_add_f32_e32 v0, v238, v0
	v_exp_f32_e32 v241, v241
	v_cndmask_b32_e64 v240, 0, v240, s[46:47]
	v_add_f32_e32 v0, v239, v0
	s_waitcnt lgkmcnt(1)
	v_mfma_f32_32x32x16_bf16 v[144:159], v[6:9], v[160:163], 0
	ds_read_b128 v[2:5], v222 offset:8192
	v_cvt_pk_bf16_f32 v237, v238, v239
	v_exp_f32_e32 v242, v242
	v_cndmask_b32_e64 v241, 0, v241, s[48:49]
	v_add_f32_e32 v0, v240, v0
	s_waitcnt lgkmcnt(1)
	v_mfma_f32_32x32x16_bf16 v[144:159], v[10:13], v[164:167], v[144:159]
	ds_read_b128 v[6:9], v223 offset:8192
	v_exp_f32_e32 v243, v243
	v_cndmask_b32_e64 v242, 0, v242, s[50:51]
	v_add_f32_e32 v0, v241, v0
	v_cvt_pk_bf16_f32 v238, v240, v241
	s_waitcnt lgkmcnt(1)
	v_mfma_f32_32x32x16_bf16 v[144:159], v[2:5], v[168:171], v[144:159]
	ds_read_b128 v[10:13], v15 offset:32768
	v_exp_f32_e32 v244, v244
	v_cndmask_b32_e64 v243, 0, v243, s[76:77]
	v_add_f32_e32 v0, v242, v0
	v_exp_f32_e32 v245, v245
	s_waitcnt lgkmcnt(1)
	v_mfma_f32_32x32x16_bf16 v[144:159], v[6:9], v[172:175], v[144:159]
	ds_read_b128 v[2:5], v15 offset:40960
	v_cndmask_b32_e64 v244, 0, v244, s[84:85]
	v_add_f32_e32 v0, v243, v0
	v_cvt_pk_bf16_f32 v239, v242, v243
	v_exp_f32_e32 v246, v246
	s_waitcnt lgkmcnt(1)
	v_mfma_f32_32x32x16_bf16 v[64:79], v[10:13], v[236:239], v[64:79]
	ds_read_b128 v[6:9], v15 offset:49152
	s_add_i32 m0, s1, 0x400
	s_nop 0
	global_load_lds_dwordx4 v208, s[74:75]
	v_cndmask_b32_e64 v245, 0, v245, s[86:87]
	v_add_f32_e32 v0, v244, v0
	v_exp_f32_e32 v247, v247
	v_cndmask_b32_e64 v246, 0, v246, s[88:89]
	s_waitcnt lgkmcnt(1)
	v_mfma_f32_32x32x16_bf16 v[48:63], v[2:5], v[236:239], v[48:63]
	ds_read_b128 v[10:13], v15 offset:57344
	v_add_f32_e32 v0, v245, v0
	v_cvt_pk_bf16_f32 v240, v244, v245
	v_exp_f32_e32 v248, v248
	v_cndmask_b32_e64 v247, 0, v247, s[90:91]
	s_waitcnt lgkmcnt(1)
	v_mfma_f32_32x32x16_bf16 v[32:47], v[6:9], v[236:239], v[32:47]
	v_xor_b32_e32 v253, 32, v15
	ds_read_b128 v[2:5], v253 offset:32768
	v_add_f32_e32 v0, v246, v0
	v_exp_f32_e32 v249, v249
	v_cndmask_b32_e64 v248, 0, v248, s[92:93]
	v_add_f32_e32 v0, v247, v0
	s_waitcnt lgkmcnt(1)
	v_mfma_f32_32x32x16_bf16 v[16:31], v[10:13], v[236:239], v[16:31]
	ds_read_b128 v[6:9], v253 offset:40960
	v_cvt_pk_bf16_f32 v241, v246, v247
	v_exp_f32_e32 v250, v250
	v_cndmask_b32_e64 v249, 0, v249, s[94:95]
	v_add_f32_e32 v0, v248, v0
	v_exp_f32_e32 v251, v251
	v_cndmask_b32_e64 v250, 0, v250, s[96:97]
	v_add_f32_e32 v0, v249, v0
	v_cvt_pk_bf16_f32 v242, v248, v249
	v_cndmask_b32_e64 v251, 0, v251, vcc
	v_add_f32_e32 v0, v250, v0
	v_add_f32_e32 v0, v251, v0
	v_cvt_pk_bf16_f32 v243, v250, v251
	s_waitcnt lgkmcnt(1)
	s_nop 0
	v_mfma_f32_32x32x16_bf16 v[64:79], v[2:5], v[240:243], v[64:79]
	ds_read_b128 v[10:13], v253 offset:49152
	v_add_f32_e32 v196, v196, v0
	v_subrev_u32_e32 v219, 32, v218
	v_cmp_ge_i32_e64 s[4:5], v219, 0
	v_cmp_ge_i32_e64 s[6:7], v219, 1
	s_waitcnt lgkmcnt(1)
	v_mfma_f32_32x32x16_bf16 v[48:63], v[6:9], v[240:243], v[48:63]
	ds_read_b128 v[2:5], v253 offset:57344
	v_cmp_ge_i32_e64 s[10:11], v219, 2
	v_cmp_ge_i32_e64 s[20:21], v219, 3
	v_cmp_ge_i32_e64 s[46:47], v219, 4
	v_cmp_ge_i32_e64 s[48:49], v219, 5
	s_waitcnt lgkmcnt(1)
	v_mfma_f32_32x32x16_bf16 v[32:47], v[10:13], v[240:243], v[32:47]
	ds_read_b128 v[6:9], v225 offset:8192
	v_cmp_ge_i32_e64 s[50:51], v219, 6
	v_cmp_ge_i32_e64 s[76:77], v219, 7
	v_cmp_ge_i32_e64 s[84:85], v219, 16
	v_cmp_ge_i32_e64 s[86:87], v219, 17
	s_waitcnt lgkmcnt(1)
	v_mfma_f32_32x32x16_bf16 v[16:31], v[2:5], v[240:243], v[16:31]
	ds_read_b128 v[10:13], v230 offset:8192
	v_cmp_ge_i32_e64 s[88:89], v219, 18
	v_cmp_ge_i32_e64 s[90:91], v219, 19
	v_cmp_ge_i32_e64 s[92:93], v219, 20
	v_cmp_ge_i32_e64 s[94:95], v219, 21
	s_waitcnt lgkmcnt(1)
	v_mfma_f32_32x32x16_bf16 v[236:251], v[6:9], v[176:179], 0
	ds_read_b128 v[2:5], v231 offset:8192
	s_add_i32 m0, s1, 0x8400
	s_nop 0
	global_load_lds_dwordx4 v200, s[74:75]
	v_cmp_ge_i32_e64 s[96:97], v219, 22
	v_cmp_ge_i32_e64 vcc, v219, 23
	v_exp_f32_e32 v144, v144
	v_exp_f32_e32 v145, v145
	s_waitcnt lgkmcnt(1)
	v_mfma_f32_32x32x16_bf16 v[236:251], v[10:13], v[180:183], v[236:251]
	ds_read_b128 v[6:9], v235 offset:8192
	v_cndmask_b32_e64 v144, 0, v144, s[4:5]
	v_exp_f32_e32 v146, v146
	v_cndmask_b32_e64 v145, 0, v145, s[6:7]
	v_exp_f32_e32 v147, v147
	s_waitcnt lgkmcnt(1)
	v_mfma_f32_32x32x16_bf16 v[236:251], v[2:5], v[184:187], v[236:251]
	v_xor_b32_e32 v252, 64, v15
	ds_read_b128 v[10:13], v252 offset:32768
	v_cndmask_b32_e64 v146, 0, v146, s[10:11]
	v_add_f32_e32 v0, v144, v145
	v_cvt_pk_bf16_f32 v144, v144, v145
	v_exp_f32_e32 v148, v148
	s_waitcnt lgkmcnt(1)
	v_mfma_f32_32x32x16_bf16 v[236:251], v[6:9], v[188:191], v[236:251]
	ds_read_b128 v[2:5], v252 offset:40960
	v_cndmask_b32_e64 v147, 0, v147, s[20:21]
	v_add_f32_e32 v0, v146, v0
	v_exp_f32_e32 v149, v149
	v_cndmask_b32_e64 v148, 0, v148, s[46:47]
	v_add_f32_e32 v0, v147, v0
	v_cvt_pk_bf16_f32 v145, v146, v147
	v_exp_f32_e32 v150, v150
	v_cndmask_b32_e64 v149, 0, v149, s[48:49]
	v_add_f32_e32 v0, v148, v0
	v_exp_f32_e32 v151, v151
	v_cndmask_b32_e64 v150, 0, v150, s[50:51]
	v_add_f32_e32 v0, v149, v0
	v_cvt_pk_bf16_f32 v146, v148, v149
	v_exp_f32_e32 v152, v152
	v_cndmask_b32_e64 v151, 0, v151, s[76:77]
	v_add_f32_e32 v0, v150, v0
	v_exp_f32_e32 v153, v153
	v_cndmask_b32_e64 v152, 0, v152, s[84:85]
	v_add_f32_e32 v0, v151, v0
	v_cvt_pk_bf16_f32 v147, v150, v151
	s_waitcnt lgkmcnt(1)
	s_nop 0
	v_mfma_f32_32x32x16_bf16 v[128:143], v[10:13], v[144:147], v[128:143]
	ds_read_b128 v[6:9], v252 offset:49152
	v_exp_f32_e32 v154, v154
	v_cndmask_b32_e64 v153, 0, v153, s[86:87]
	v_add_f32_e32 v0, v152, v0
	v_exp_f32_e32 v155, v155
	s_waitcnt lgkmcnt(1)
	v_mfma_f32_32x32x16_bf16 v[112:127], v[2:5], v[144:147], v[112:127]
	ds_read_b128 v[10:13], v252 offset:57344
	v_cndmask_b32_e64 v154, 0, v154, s[88:89]
	v_add_f32_e32 v0, v153, v0
	v_cvt_pk_bf16_f32 v148, v152, v153
	v_exp_f32_e32 v156, v156
	s_waitcnt lgkmcnt(1)
	v_mfma_f32_32x32x16_bf16 v[96:111], v[6:9], v[144:147], v[96:111]
	v_xor_b32_e32 v253, 0x60, v15
	ds_read_b128 v[2:5], v253 offset:32768
	v_cndmask_b32_e64 v155, 0, v155, s[90:91]
	v_add_f32_e32 v0, v154, v0
	v_exp_f32_e32 v157, v157
	v_cndmask_b32_e64 v156, 0, v156, s[92:93]
	s_waitcnt lgkmcnt(1)
	v_mfma_f32_32x32x16_bf16 v[80:95], v[10:13], v[144:147], v[80:95]
	ds_read_b128 v[6:9], v253 offset:40960
	v_add_f32_e32 v0, v155, v0
	v_cvt_pk_bf16_f32 v149, v154, v155
	v_exp_f32_e32 v158, v158
	v_cndmask_b32_e64 v157, 0, v157, s[94:95]
	v_add_f32_e32 v0, v156, v0
	v_exp_f32_e32 v159, v159
	v_cndmask_b32_e64 v158, 0, v158, s[96:97]
	v_add_f32_e32 v0, v157, v0
	v_cvt_pk_bf16_f32 v150, v156, v157
	v_cndmask_b32_e64 v159, 0, v159, vcc
	v_add_f32_e32 v0, v158, v0
	v_add_f32_e32 v0, v159, v0
	v_cvt_pk_bf16_f32 v151, v158, v159
	s_waitcnt lgkmcnt(1)
	s_nop 0
	v_mfma_f32_32x32x16_bf16 v[128:143], v[2:5], v[148:151], v[128:143]
	ds_read_b128 v[10:13], v253 offset:49152
	s_add_i32 m0, s1, 0x800
	s_nop 0
	global_load_lds_dwordx4 v210, s[74:75]
	v_add_f32_e32 v197, v197, v0
	v_exp_f32_e32 v236, v236
	v_exp_f32_e32 v237, v237
	v_cndmask_b32_e64 v236, 0, v236, s[4:5]
	s_waitcnt lgkmcnt(1)
	v_mfma_f32_32x32x16_bf16 v[112:127], v[6:9], v[148:151], v[112:127]
	ds_read_b128 v[2:5], v253 offset:57344
	v_exp_f32_e32 v238, v238
	v_cndmask_b32_e64 v237, 0, v237, s[6:7]
	v_exp_f32_e32 v239, v239
	v_cndmask_b32_e64 v238, 0, v238, s[10:11]
	s_waitcnt lgkmcnt(1)
	v_mfma_f32_32x32x16_bf16 v[96:111], v[10:13], v[148:151], v[96:111]
	ds_read_b128 v[6:9], v14 offset:16384
	v_add_f32_e32 v0, v236, v237
	v_cvt_pk_bf16_f32 v236, v236, v237
	v_exp_f32_e32 v240, v240
	v_cndmask_b32_e64 v239, 0, v239, s[20:21]
	s_waitcnt lgkmcnt(1)
	v_mfma_f32_32x32x16_bf16 v[80:95], v[2:5], v[148:151], v[80:95]
	ds_read_b128 v[10:13], v217 offset:16384
	v_add_f32_e32 v0, v238, v0
	v_exp_f32_e32 v241, v241
	v_cndmask_b32_e64 v240, 0, v240, s[46:47]
	v_add_f32_e32 v0, v239, v0
	s_waitcnt lgkmcnt(1)
	v_mfma_f32_32x32x16_bf16 v[144:159], v[6:9], v[160:163], 0
	ds_read_b128 v[2:5], v222 offset:16384
	v_cvt_pk_bf16_f32 v237, v238, v239
	v_exp_f32_e32 v242, v242
	v_cndmask_b32_e64 v241, 0, v241, s[48:49]
	v_add_f32_e32 v0, v240, v0
	s_waitcnt lgkmcnt(1)
	v_mfma_f32_32x32x16_bf16 v[144:159], v[10:13], v[164:167], v[144:159]
	ds_read_b128 v[6:9], v223 offset:16384
	v_exp_f32_e32 v243, v243
	v_cndmask_b32_e64 v242, 0, v242, s[50:51]
	v_add_f32_e32 v0, v241, v0
	v_cvt_pk_bf16_f32 v238, v240, v241
	s_waitcnt lgkmcnt(1)
	v_mfma_f32_32x32x16_bf16 v[144:159], v[2:5], v[168:171], v[144:159]
	v_xor_b32_e32 v252, 64, v15
	ds_read_b128 v[10:13], v252 offset:32768
	v_exp_f32_e32 v244, v244
	v_cndmask_b32_e64 v243, 0, v243, s[76:77]
	v_add_f32_e32 v0, v242, v0
	v_exp_f32_e32 v245, v245
	s_waitcnt lgkmcnt(1)
	v_mfma_f32_32x32x16_bf16 v[144:159], v[6:9], v[172:175], v[144:159]
	ds_read_b128 v[2:5], v252 offset:40960
	v_cndmask_b32_e64 v244, 0, v244, s[84:85]
	v_add_f32_e32 v0, v243, v0
	v_cvt_pk_bf16_f32 v239, v242, v243
	v_exp_f32_e32 v246, v246
	s_waitcnt lgkmcnt(1)
	v_mfma_f32_32x32x16_bf16 v[64:79], v[10:13], v[236:239], v[64:79]
	ds_read_b128 v[6:9], v252 offset:49152
	s_add_i32 m0, s1, 0x8800
	s_nop 0
	global_load_lds_dwordx4 v202, s[74:75]
	v_cndmask_b32_e64 v245, 0, v245, s[86:87]
	v_add_f32_e32 v0, v244, v0
	v_exp_f32_e32 v247, v247
	v_cndmask_b32_e64 v246, 0, v246, s[88:89]
	s_waitcnt lgkmcnt(1)
	v_mfma_f32_32x32x16_bf16 v[48:63], v[2:5], v[236:239], v[48:63]
	ds_read_b128 v[10:13], v252 offset:57344
	v_add_f32_e32 v0, v245, v0
	v_cvt_pk_bf16_f32 v240, v244, v245
	v_exp_f32_e32 v248, v248
	v_cndmask_b32_e64 v247, 0, v247, s[90:91]
	s_waitcnt lgkmcnt(1)
	v_mfma_f32_32x32x16_bf16 v[32:47], v[6:9], v[236:239], v[32:47]
	v_xor_b32_e32 v253, 0x60, v15
	ds_read_b128 v[2:5], v253 offset:32768
	v_add_f32_e32 v0, v246, v0
	v_exp_f32_e32 v249, v249
	v_cndmask_b32_e64 v248, 0, v248, s[92:93]
	v_add_f32_e32 v0, v247, v0
	s_waitcnt lgkmcnt(1)
	v_mfma_f32_32x32x16_bf16 v[16:31], v[10:13], v[236:239], v[16:31]
	ds_read_b128 v[6:9], v253 offset:40960
	v_cvt_pk_bf16_f32 v241, v246, v247
	v_exp_f32_e32 v250, v250
	v_cndmask_b32_e64 v249, 0, v249, s[94:95]
	v_add_f32_e32 v0, v248, v0
	v_exp_f32_e32 v251, v251
	v_cndmask_b32_e64 v250, 0, v250, s[96:97]
	v_add_f32_e32 v0, v249, v0
	v_cvt_pk_bf16_f32 v242, v248, v249
	v_cndmask_b32_e64 v251, 0, v251, vcc
	v_add_f32_e32 v0, v250, v0
	v_add_f32_e32 v0, v251, v0
	v_cvt_pk_bf16_f32 v243, v250, v251
	s_waitcnt lgkmcnt(1)
	s_nop 0
	v_mfma_f32_32x32x16_bf16 v[64:79], v[2:5], v[240:243], v[64:79]
	ds_read_b128 v[10:13], v253 offset:49152
	v_add_f32_e32 v196, v196, v0
	v_subrev_u32_e32 v219, 64, v218
	v_cmp_ge_i32_e64 s[4:5], v219, 0
	v_cmp_ge_i32_e64 s[6:7], v219, 1
	s_waitcnt lgkmcnt(1)
	v_mfma_f32_32x32x16_bf16 v[48:63], v[6:9], v[240:243], v[48:63]
	ds_read_b128 v[2:5], v253 offset:57344
	v_cmp_ge_i32_e64 s[10:11], v219, 2
	v_cmp_ge_i32_e64 s[20:21], v219, 3
	v_cmp_ge_i32_e64 s[46:47], v219, 4
	v_cmp_ge_i32_e64 s[48:49], v219, 5
	s_waitcnt lgkmcnt(1)
	v_mfma_f32_32x32x16_bf16 v[32:47], v[10:13], v[240:243], v[32:47]
	ds_read_b128 v[6:9], v225 offset:16384
	v_cmp_ge_i32_e64 s[50:51], v219, 6
	v_cmp_ge_i32_e64 s[76:77], v219, 7
	v_cmp_ge_i32_e64 s[84:85], v219, 16
	v_cmp_ge_i32_e64 s[86:87], v219, 17
	s_waitcnt lgkmcnt(1)
	v_mfma_f32_32x32x16_bf16 v[16:31], v[2:5], v[240:243], v[16:31]
	ds_read_b128 v[10:13], v230 offset:16384
	v_cmp_ge_i32_e64 s[88:89], v219, 18
	v_cmp_ge_i32_e64 s[90:91], v219, 19
	v_cmp_ge_i32_e64 s[92:93], v219, 20
	v_cmp_ge_i32_e64 s[94:95], v219, 21
	s_waitcnt lgkmcnt(1)
	v_mfma_f32_32x32x16_bf16 v[236:251], v[6:9], v[176:179], 0
	ds_read_b128 v[2:5], v231 offset:16384
	s_add_i32 m0, s1, 0xc00
	s_nop 0
	global_load_lds_dwordx4 v212, s[74:75]
	v_cmp_ge_i32_e64 s[96:97], v219, 22
	v_cmp_ge_i32_e64 vcc, v219, 23
	v_exp_f32_e32 v144, v144
	v_exp_f32_e32 v145, v145
	s_waitcnt lgkmcnt(1)
	v_mfma_f32_32x32x16_bf16 v[236:251], v[10:13], v[180:183], v[236:251]
	ds_read_b128 v[6:9], v235 offset:16384
	v_cndmask_b32_e64 v144, 0, v144, s[4:5]
	v_exp_f32_e32 v146, v146
	v_cndmask_b32_e64 v145, 0, v145, s[6:7]
	v_exp_f32_e32 v147, v147
	s_waitcnt lgkmcnt(1)
	v_mfma_f32_32x32x16_bf16 v[236:251], v[2:5], v[184:187], v[236:251]
	v_xor_b32_e32 v252, 0x80, v15
	ds_read_b128 v[10:13], v252 offset:32768
	v_cndmask_b32_e64 v146, 0, v146, s[10:11]
	v_add_f32_e32 v0, v144, v145
	v_cvt_pk_bf16_f32 v144, v144, v145
	v_exp_f32_e32 v148, v148
	s_waitcnt lgkmcnt(1)
	v_mfma_f32_32x32x16_bf16 v[236:251], v[6:9], v[188:191], v[236:251]
	ds_read_b128 v[2:5], v252 offset:40960
	v_cndmask_b32_e64 v147, 0, v147, s[20:21]
	v_add_f32_e32 v0, v146, v0
	v_exp_f32_e32 v149, v149
	v_cndmask_b32_e64 v148, 0, v148, s[46:47]
	v_add_f32_e32 v0, v147, v0
	v_cvt_pk_bf16_f32 v145, v146, v147
	v_exp_f32_e32 v150, v150
	v_cndmask_b32_e64 v149, 0, v149, s[48:49]
	v_add_f32_e32 v0, v148, v0
	v_exp_f32_e32 v151, v151
	v_cndmask_b32_e64 v150, 0, v150, s[50:51]
	v_add_f32_e32 v0, v149, v0
	v_cvt_pk_bf16_f32 v146, v148, v149
	v_exp_f32_e32 v152, v152
	v_cndmask_b32_e64 v151, 0, v151, s[76:77]
	v_add_f32_e32 v0, v150, v0
	v_exp_f32_e32 v153, v153
	v_cndmask_b32_e64 v152, 0, v152, s[84:85]
	v_add_f32_e32 v0, v151, v0
	v_cvt_pk_bf16_f32 v147, v150, v151
	s_waitcnt lgkmcnt(1)
	s_nop 0
	v_mfma_f32_32x32x16_bf16 v[128:143], v[10:13], v[144:147], v[128:143]
	ds_read_b128 v[6:9], v252 offset:49152
	v_exp_f32_e32 v154, v154
	v_cndmask_b32_e64 v153, 0, v153, s[86:87]
	v_add_f32_e32 v0, v152, v0
	v_exp_f32_e32 v155, v155
	s_waitcnt lgkmcnt(1)
	v_mfma_f32_32x32x16_bf16 v[112:127], v[2:5], v[144:147], v[112:127]
	ds_read_b128 v[10:13], v252 offset:57344
	v_cndmask_b32_e64 v154, 0, v154, s[88:89]
	v_add_f32_e32 v0, v153, v0
	v_cvt_pk_bf16_f32 v148, v152, v153
	v_exp_f32_e32 v156, v156
	s_waitcnt lgkmcnt(1)
	v_mfma_f32_32x32x16_bf16 v[96:111], v[6:9], v[144:147], v[96:111]
	v_xor_b32_e32 v253, 0xa0, v15
	ds_read_b128 v[2:5], v253 offset:32768
	v_cndmask_b32_e64 v155, 0, v155, s[90:91]
	v_add_f32_e32 v0, v154, v0
	v_exp_f32_e32 v157, v157
	v_cndmask_b32_e64 v156, 0, v156, s[92:93]
	s_waitcnt lgkmcnt(1)
	v_mfma_f32_32x32x16_bf16 v[80:95], v[10:13], v[144:147], v[80:95]
	ds_read_b128 v[6:9], v253 offset:40960
	v_add_f32_e32 v0, v155, v0
	v_cvt_pk_bf16_f32 v149, v154, v155
	v_exp_f32_e32 v158, v158
	v_cndmask_b32_e64 v157, 0, v157, s[94:95]
	v_add_f32_e32 v0, v156, v0
	v_exp_f32_e32 v159, v159
	v_cndmask_b32_e64 v158, 0, v158, s[96:97]
	v_add_f32_e32 v0, v157, v0
	v_cvt_pk_bf16_f32 v150, v156, v157
	v_cndmask_b32_e64 v159, 0, v159, vcc
	v_add_f32_e32 v0, v158, v0
	v_add_f32_e32 v0, v159, v0
	v_cvt_pk_bf16_f32 v151, v158, v159
	s_waitcnt lgkmcnt(1)
	s_nop 0
	v_mfma_f32_32x32x16_bf16 v[128:143], v[2:5], v[148:151], v[128:143]
	ds_read_b128 v[10:13], v253 offset:49152
	s_add_i32 m0, s1, 0x8c00
	s_nop 0
	global_load_lds_dwordx4 v204, s[74:75]
	v_add_f32_e32 v197, v197, v0
	v_exp_f32_e32 v236, v236
	v_exp_f32_e32 v237, v237
	v_cndmask_b32_e64 v236, 0, v236, s[4:5]
	s_waitcnt lgkmcnt(1)
	v_mfma_f32_32x32x16_bf16 v[112:127], v[6:9], v[148:151], v[112:127]
	ds_read_b128 v[2:5], v253 offset:57344
	v_exp_f32_e32 v238, v238
	v_cndmask_b32_e64 v237, 0, v237, s[6:7]
	v_exp_f32_e32 v239, v239
	v_cndmask_b32_e64 v238, 0, v238, s[10:11]
	s_waitcnt lgkmcnt(1)
	v_mfma_f32_32x32x16_bf16 v[96:111], v[10:13], v[148:151], v[96:111]
	ds_read_b128 v[6:9], v14 offset:24576
	v_add_f32_e32 v0, v236, v237
	v_cvt_pk_bf16_f32 v236, v236, v237
	v_exp_f32_e32 v240, v240
	v_cndmask_b32_e64 v239, 0, v239, s[20:21]
	s_waitcnt lgkmcnt(1)
	v_mfma_f32_32x32x16_bf16 v[80:95], v[2:5], v[148:151], v[80:95]
	ds_read_b128 v[10:13], v217 offset:24576
	v_add_f32_e32 v0, v238, v0
	v_exp_f32_e32 v241, v241
	v_cndmask_b32_e64 v240, 0, v240, s[46:47]
	v_add_f32_e32 v0, v239, v0
	s_waitcnt lgkmcnt(1)
	v_mfma_f32_32x32x16_bf16 v[144:159], v[6:9], v[160:163], 0
	ds_read_b128 v[2:5], v222 offset:24576
	v_cvt_pk_bf16_f32 v237, v238, v239
	v_exp_f32_e32 v242, v242
	v_cndmask_b32_e64 v241, 0, v241, s[48:49]
	v_add_f32_e32 v0, v240, v0
	s_waitcnt lgkmcnt(1)
	v_mfma_f32_32x32x16_bf16 v[144:159], v[10:13], v[164:167], v[144:159]
	ds_read_b128 v[6:9], v223 offset:24576
	v_exp_f32_e32 v243, v243
	v_cndmask_b32_e64 v242, 0, v242, s[50:51]
	v_add_f32_e32 v0, v241, v0
	v_cvt_pk_bf16_f32 v238, v240, v241
	s_waitcnt lgkmcnt(1)
	v_mfma_f32_32x32x16_bf16 v[144:159], v[2:5], v[168:171], v[144:159]
	v_xor_b32_e32 v252, 0x80, v15
	ds_read_b128 v[10:13], v252 offset:32768
	v_exp_f32_e32 v244, v244
	v_cndmask_b32_e64 v243, 0, v243, s[76:77]
	v_add_f32_e32 v0, v242, v0
	v_exp_f32_e32 v245, v245
	s_waitcnt lgkmcnt(1)
	v_mfma_f32_32x32x16_bf16 v[144:159], v[6:9], v[172:175], v[144:159]
	ds_read_b128 v[2:5], v252 offset:40960
	v_cndmask_b32_e64 v244, 0, v244, s[84:85]
	v_add_f32_e32 v0, v243, v0
	v_cvt_pk_bf16_f32 v239, v242, v243
	v_exp_f32_e32 v246, v246
	s_waitcnt lgkmcnt(1)
	v_mfma_f32_32x32x16_bf16 v[64:79], v[10:13], v[236:239], v[64:79]
	ds_read_b128 v[6:9], v252 offset:49152
	v_cndmask_b32_e64 v245, 0, v245, s[86:87]
	v_add_f32_e32 v0, v244, v0
	v_exp_f32_e32 v247, v247
	v_cndmask_b32_e64 v246, 0, v246, s[88:89]
	s_waitcnt lgkmcnt(1)
	v_mfma_f32_32x32x16_bf16 v[48:63], v[2:5], v[236:239], v[48:63]
	ds_read_b128 v[10:13], v252 offset:57344
	v_add_f32_e32 v0, v245, v0
	v_cvt_pk_bf16_f32 v240, v244, v245
	v_exp_f32_e32 v248, v248
	v_cndmask_b32_e64 v247, 0, v247, s[90:91]
	s_waitcnt lgkmcnt(1)
	v_mfma_f32_32x32x16_bf16 v[32:47], v[6:9], v[236:239], v[32:47]
	v_xor_b32_e32 v253, 0xa0, v15
	ds_read_b128 v[2:5], v253 offset:32768
	v_add_f32_e32 v0, v246, v0
	v_exp_f32_e32 v249, v249
	v_cndmask_b32_e64 v248, 0, v248, s[92:93]
	v_add_f32_e32 v0, v247, v0
	s_waitcnt lgkmcnt(1)
	v_mfma_f32_32x32x16_bf16 v[16:31], v[10:13], v[236:239], v[16:31]
	ds_read_b128 v[6:9], v253 offset:40960
	v_cvt_pk_bf16_f32 v241, v246, v247
	v_exp_f32_e32 v250, v250
	v_cndmask_b32_e64 v249, 0, v249, s[94:95]
	v_add_f32_e32 v0, v248, v0
	v_exp_f32_e32 v251, v251
	v_cndmask_b32_e64 v250, 0, v250, s[96:97]
	v_add_f32_e32 v0, v249, v0
	v_cvt_pk_bf16_f32 v242, v248, v249
	v_cndmask_b32_e64 v251, 0, v251, vcc
	v_add_f32_e32 v0, v250, v0
	v_add_f32_e32 v0, v251, v0
	v_cvt_pk_bf16_f32 v243, v250, v251
	s_waitcnt lgkmcnt(1)
	s_nop 0
	v_mfma_f32_32x32x16_bf16 v[64:79], v[2:5], v[240:243], v[64:79]
	ds_read_b128 v[10:13], v253 offset:49152
	v_add_f32_e32 v196, v196, v0
	v_subrev_u32_e32 v219, 0x60, v218
	v_cmp_ge_i32_e64 s[4:5], v219, 0
	v_cmp_ge_i32_e64 s[6:7], v219, 1
	s_waitcnt lgkmcnt(1)
	v_mfma_f32_32x32x16_bf16 v[48:63], v[6:9], v[240:243], v[48:63]
	ds_read_b128 v[2:5], v253 offset:57344
	v_cmp_ge_i32_e64 s[10:11], v219, 2
	v_cmp_ge_i32_e64 s[20:21], v219, 3
	v_cmp_ge_i32_e64 s[46:47], v219, 4
	v_cmp_ge_i32_e64 s[48:49], v219, 5
	s_waitcnt lgkmcnt(1)
	v_mfma_f32_32x32x16_bf16 v[32:47], v[10:13], v[240:243], v[32:47]
	ds_read_b128 v[6:9], v225 offset:24576
	v_cmp_ge_i32_e64 s[50:51], v219, 6
	v_cmp_ge_i32_e64 s[76:77], v219, 7
	v_cmp_ge_i32_e64 s[84:85], v219, 16
	v_cmp_ge_i32_e64 s[86:87], v219, 17
	s_waitcnt lgkmcnt(1)
	v_mfma_f32_32x32x16_bf16 v[16:31], v[2:5], v[240:243], v[16:31]
	ds_read_b128 v[10:13], v230 offset:24576
	v_cmp_ge_i32_e64 s[88:89], v219, 18
	v_cmp_ge_i32_e64 s[90:91], v219, 19
	v_cmp_ge_i32_e64 s[92:93], v219, 20
	v_cmp_ge_i32_e64 s[94:95], v219, 21
	s_waitcnt lgkmcnt(1)
	v_mfma_f32_32x32x16_bf16 v[236:251], v[6:9], v[176:179], 0
	ds_read_b128 v[2:5], v231 offset:24576
	v_cmp_ge_i32_e64 s[96:97], v219, 22
	v_cmp_ge_i32_e64 vcc, v219, 23
	v_exp_f32_e32 v144, v144
	v_exp_f32_e32 v145, v145
	s_waitcnt lgkmcnt(1)
	v_mfma_f32_32x32x16_bf16 v[236:251], v[10:13], v[180:183], v[236:251]
	ds_read_b128 v[6:9], v235 offset:24576
	v_cndmask_b32_e64 v144, 0, v144, s[4:5]
	v_exp_f32_e32 v146, v146
	v_cndmask_b32_e64 v145, 0, v145, s[6:7]
	v_exp_f32_e32 v147, v147
	s_waitcnt lgkmcnt(1)
	v_mfma_f32_32x32x16_bf16 v[236:251], v[2:5], v[184:187], v[236:251]
	v_xor_b32_e32 v252, 0xc0, v15
	ds_read_b128 v[10:13], v252 offset:32768
	v_cndmask_b32_e64 v146, 0, v146, s[10:11]
	v_add_f32_e32 v0, v144, v145
	v_cvt_pk_bf16_f32 v144, v144, v145
	v_exp_f32_e32 v148, v148
	s_waitcnt lgkmcnt(1)
	v_mfma_f32_32x32x16_bf16 v[236:251], v[6:9], v[188:191], v[236:251]
	ds_read_b128 v[2:5], v252 offset:40960
	v_cndmask_b32_e64 v147, 0, v147, s[20:21]
	v_add_f32_e32 v0, v146, v0
	v_exp_f32_e32 v149, v149
	v_cndmask_b32_e64 v148, 0, v148, s[46:47]
	v_add_f32_e32 v0, v147, v0
	v_cvt_pk_bf16_f32 v145, v146, v147
	v_exp_f32_e32 v150, v150
	v_cndmask_b32_e64 v149, 0, v149, s[48:49]
	v_add_f32_e32 v0, v148, v0
	v_exp_f32_e32 v151, v151
	v_cndmask_b32_e64 v150, 0, v150, s[50:51]
	v_add_f32_e32 v0, v149, v0
	v_cvt_pk_bf16_f32 v146, v148, v149
	v_exp_f32_e32 v152, v152
	v_cndmask_b32_e64 v151, 0, v151, s[76:77]
	v_add_f32_e32 v0, v150, v0
	v_exp_f32_e32 v153, v153
	v_cndmask_b32_e64 v152, 0, v152, s[84:85]
	v_add_f32_e32 v0, v151, v0
	v_cvt_pk_bf16_f32 v147, v150, v151
	s_waitcnt lgkmcnt(1)
	s_nop 0
	v_mfma_f32_32x32x16_bf16 v[128:143], v[10:13], v[144:147], v[128:143]
	ds_read_b128 v[6:9], v252 offset:49152
	v_exp_f32_e32 v154, v154
	v_cndmask_b32_e64 v153, 0, v153, s[86:87]
	v_add_f32_e32 v0, v152, v0
	v_exp_f32_e32 v155, v155
	s_waitcnt lgkmcnt(1)
	v_mfma_f32_32x32x16_bf16 v[112:127], v[2:5], v[144:147], v[112:127]
	ds_read_b128 v[10:13], v252 offset:57344
	v_cndmask_b32_e64 v154, 0, v154, s[88:89]
	v_add_f32_e32 v0, v153, v0
	v_cvt_pk_bf16_f32 v148, v152, v153
	v_exp_f32_e32 v156, v156
	s_waitcnt lgkmcnt(1)
	v_mfma_f32_32x32x16_bf16 v[96:111], v[6:9], v[144:147], v[96:111]
	v_xor_b32_e32 v253, 0xe0, v15
	ds_read_b128 v[2:5], v253 offset:32768
	v_cndmask_b32_e64 v155, 0, v155, s[90:91]
	v_add_f32_e32 v0, v154, v0
	v_exp_f32_e32 v157, v157
	v_cndmask_b32_e64 v156, 0, v156, s[92:93]
	s_waitcnt lgkmcnt(1)
	v_mfma_f32_32x32x16_bf16 v[80:95], v[10:13], v[144:147], v[80:95]
	ds_read_b128 v[6:9], v253 offset:40960
	v_add_f32_e32 v0, v155, v0
	v_cvt_pk_bf16_f32 v149, v154, v155
	v_exp_f32_e32 v158, v158
	v_cndmask_b32_e64 v157, 0, v157, s[94:95]
	v_add_f32_e32 v0, v156, v0
	v_exp_f32_e32 v159, v159
	v_cndmask_b32_e64 v158, 0, v158, s[96:97]
	v_add_f32_e32 v0, v157, v0
	v_cvt_pk_bf16_f32 v150, v156, v157
	v_cndmask_b32_e64 v159, 0, v159, vcc
	v_add_f32_e32 v0, v158, v0
	v_add_f32_e32 v0, v159, v0
	v_cvt_pk_bf16_f32 v151, v158, v159
	s_waitcnt lgkmcnt(1)
	s_nop 0
	v_mfma_f32_32x32x16_bf16 v[128:143], v[2:5], v[148:151], v[128:143]
	ds_read_b128 v[10:13], v253 offset:49152
	v_add_f32_e32 v197, v197, v0
	v_exp_f32_e32 v236, v236
	v_exp_f32_e32 v237, v237
	v_cndmask_b32_e64 v236, 0, v236, s[4:5]
	s_waitcnt lgkmcnt(1)
	v_mfma_f32_32x32x16_bf16 v[112:127], v[6:9], v[148:151], v[112:127]
	ds_read_b128 v[2:5], v253 offset:57344
	v_exp_f32_e32 v238, v238
	v_cndmask_b32_e64 v237, 0, v237, s[6:7]
	v_exp_f32_e32 v239, v239
	v_cndmask_b32_e64 v238, 0, v238, s[10:11]
	s_waitcnt lgkmcnt(1)
	v_mfma_f32_32x32x16_bf16 v[96:111], v[10:13], v[148:151], v[96:111]
	v_xor_b32_e32 v252, 0xc0, v15
	ds_read_b128 v[6:9], v252 offset:32768
	v_add_f32_e32 v0, v236, v237
	v_cvt_pk_bf16_f32 v236, v236, v237
	v_exp_f32_e32 v240, v240
	v_cndmask_b32_e64 v239, 0, v239, s[20:21]
	s_waitcnt lgkmcnt(1)
	v_mfma_f32_32x32x16_bf16 v[80:95], v[2:5], v[148:151], v[80:95]
	ds_read_b128 v[10:13], v252 offset:40960
	v_add_f32_e32 v0, v238, v0
	v_exp_f32_e32 v241, v241
	v_cndmask_b32_e64 v240, 0, v240, s[46:47]
	v_add_f32_e32 v0, v239, v0
	v_cvt_pk_bf16_f32 v237, v238, v239
	v_exp_f32_e32 v242, v242
	v_cndmask_b32_e64 v241, 0, v241, s[48:49]
	v_add_f32_e32 v0, v240, v0
	v_exp_f32_e32 v243, v243
	v_cndmask_b32_e64 v242, 0, v242, s[50:51]
	v_add_f32_e32 v0, v241, v0
	v_cvt_pk_bf16_f32 v238, v240, v241
	v_exp_f32_e32 v244, v244
	v_cndmask_b32_e64 v243, 0, v243, s[76:77]
	v_add_f32_e32 v0, v242, v0
	v_exp_f32_e32 v245, v245
	v_cndmask_b32_e64 v244, 0, v244, s[84:85]
	v_add_f32_e32 v0, v243, v0
	v_cvt_pk_bf16_f32 v239, v242, v243
	s_waitcnt lgkmcnt(1)
	s_nop 0
	v_mfma_f32_32x32x16_bf16 v[64:79], v[6:9], v[236:239], v[64:79]
	ds_read_b128 v[2:5], v252 offset:49152
	v_exp_f32_e32 v246, v246
	v_cndmask_b32_e64 v245, 0, v245, s[86:87]
	v_add_f32_e32 v0, v244, v0
	v_exp_f32_e32 v247, v247
	s_waitcnt lgkmcnt(1)
	v_mfma_f32_32x32x16_bf16 v[48:63], v[10:13], v[236:239], v[48:63]
	ds_read_b128 v[6:9], v252 offset:57344
	v_cndmask_b32_e64 v246, 0, v246, s[88:89]
	v_add_f32_e32 v0, v245, v0
	v_cvt_pk_bf16_f32 v240, v244, v245
	v_exp_f32_e32 v248, v248
	s_waitcnt lgkmcnt(1)
	v_mfma_f32_32x32x16_bf16 v[32:47], v[2:5], v[236:239], v[32:47]
	v_xor_b32_e32 v253, 0xe0, v15
	ds_read_b128 v[10:13], v253 offset:32768
	v_cndmask_b32_e64 v247, 0, v247, s[90:91]
	v_add_f32_e32 v0, v246, v0
	v_exp_f32_e32 v249, v249
	v_cndmask_b32_e64 v248, 0, v248, s[92:93]
	s_waitcnt lgkmcnt(1)
	v_mfma_f32_32x32x16_bf16 v[16:31], v[6:9], v[236:239], v[16:31]
	ds_read_b128 v[2:5], v253 offset:40960
	v_add_f32_e32 v0, v247, v0
	v_cvt_pk_bf16_f32 v241, v246, v247
	v_exp_f32_e32 v250, v250
	v_cndmask_b32_e64 v249, 0, v249, s[94:95]
	v_add_f32_e32 v0, v248, v0
	v_exp_f32_e32 v251, v251
	v_cndmask_b32_e64 v250, 0, v250, s[96:97]
	v_add_f32_e32 v0, v249, v0
	v_cvt_pk_bf16_f32 v242, v248, v249
	v_cndmask_b32_e64 v251, 0, v251, vcc
	v_add_f32_e32 v0, v250, v0
	v_add_f32_e32 v0, v251, v0
	v_cvt_pk_bf16_f32 v243, v250, v251
	s_waitcnt lgkmcnt(1)
	s_nop 0
	v_mfma_f32_32x32x16_bf16 v[64:79], v[10:13], v[240:243], v[64:79]
	ds_read_b128 v[6:9], v253 offset:49152
	v_add_f32_e32 v196, v196, v0
	s_waitcnt lgkmcnt(1)
	v_mfma_f32_32x32x16_bf16 v[48:63], v[2:5], v[240:243], v[48:63]
	ds_read_b128 v[10:13], v253 offset:57344
	s_waitcnt lgkmcnt(1)
	v_mfma_f32_32x32x16_bf16 v[32:47], v[6:9], v[240:243], v[32:47]
	s_waitcnt lgkmcnt(0)
	v_mfma_f32_32x32x16_bf16 v[16:31], v[10:13], v[240:243], v[16:31]
	s_branch .LBB0_420
.Ldiff_fast0:
	s_lshl_b32 s1, s0, 16
	v_add3_u32 v14, s1, v215, v216
	v_add3_u32 v15, s1, v195, v224
	s_xor_b32 s1, s1, 0x10000
	s_add_i32 s1, s41, s1
	ds_read_b128 v[2:5], v14
	v_xor_b32_e32 v217, 32, v14
	ds_read_b128 v[6:9], v217
	v_xor_b32_e32 v222, 64, v14
	ds_read_b128 v[10:13], v222
	v_xor_b32_e32 v223, 0x60, v14
	ds_read_b128 v[218:221], v223
	s_waitcnt lgkmcnt(3)
	v_mfma_f32_32x32x16_bf16 v[144:159], v[2:5], v[160:163], 0
	v_xor_b32_e32 v225, 0x80, v14
	ds_read_b128 v[226:229], v225
	s_waitcnt lgkmcnt(3)
	v_mfma_f32_32x32x16_bf16 v[144:159], v[6:9], v[164:167], v[144:159]
	v_xor_b32_e32 v230, 0xa0, v14
	ds_read_b128 v[2:5], v230
	s_waitcnt lgkmcnt(3)
	v_mfma_f32_32x32x16_bf16 v[144:159], v[10:13], v[168:171], v[144:159]
	v_xor_b32_e32 v231, 0xc0, v14
	ds_read_b128 v[6:9], v231
	s_waitcnt lgkmcnt(3)
	v_mfma_f32_32x32x16_bf16 v[144:159], v[218:221], v[172:175], v[144:159]
	v_xor_b32_e32 v235, 0xe0, v14
	ds_read_b128 v[10:13], v235
	s_waitcnt lgkmcnt(3)
	v_mfma_f32_32x32x16_bf16 v[236:251], v[226:229], v[176:179], 0
	ds_read_b128 v[218:221], v15 offset:32768
	s_mov_b32 m0, s1
	s_nop 0
	global_load_lds_dwordx4 v206, s[74:75]
	s_waitcnt lgkmcnt(3)
	v_mfma_f32_32x32x16_bf16 v[236:251], v[2:5], v[180:183], v[236:251]
	ds_read_b128 v[226:229], v15 offset:40960
	s_nop 0
	v_exp_f32_e32 v144, v144
	v_exp_f32_e32 v145, v145
	v_exp_f32_e32 v146, v146
	v_add_f32_e32 v0, v144, v145
	v_cvt_pk_bf16_f32 v144, v144, v145
	v_exp_f32_e32 v147, v147
	v_add_f32_e32 v0, v146, v0
	v_exp_f32_e32 v148, v148
	s_waitcnt lgkmcnt(3)
	v_mfma_f32_32x32x16_bf16 v[236:251], v[6:9], v[184:187], v[236:251]
	ds_read_b128 v[2:5], v15 offset:49152
	v_add_f32_e32 v0, v147, v0
	v_cvt_pk_bf16_f32 v145, v146, v147
	v_exp_f32_e32 v149, v149
	v_add_f32_e32 v0, v148, v0
	s_waitcnt lgkmcnt(3)
	v_mfma_f32_32x32x16_bf16 v[236:251], v[10:13], v[188:191], v[236:251]
	ds_read_b128 v[6:9], v15 offset:57344
	v_exp_f32_e32 v150, v150
	v_add_f32_e32 v0, v149, v0
	v_cvt_pk_bf16_f32 v146, v148, v149
	v_exp_f32_e32 v151, v151
	v_add_f32_e32 v0, v150, v0
	v_exp_f32_e32 v152, v152
	v_add_f32_e32 v0, v151, v0
	v_cvt_pk_bf16_f32 v147, v150, v151
	s_waitcnt lgkmcnt(3)
	s_nop 0
	v_mfma_f32_32x32x16_bf16 v[128:143], v[218:221], v[144:147], v[128:143]
	v_xor_b32_e32 v252, 32, v15
	ds_read_b128 v[10:13], v252 offset:32768
	v_exp_f32_e32 v153, v153
	v_add_f32_e32 v0, v152, v0
	v_exp_f32_e32 v154, v154
	v_add_f32_e32 v0, v153, v0
	s_waitcnt lgkmcnt(3)
	v_mfma_f32_32x32x16_bf16 v[112:127], v[226:229], v[144:147], v[112:127]
	ds_read_b128 v[218:221], v252 offset:40960
	v_cvt_pk_bf16_f32 v148, v152, v153
	v_exp_f32_e32 v155, v155
	v_add_f32_e32 v0, v154, v0
	v_exp_f32_e32 v156, v156
	s_waitcnt lgkmcnt(3)
	v_mfma_f32_32x32x16_bf16 v[96:111], v[2:5], v[144:147], v[96:111]
	ds_read_b128 v[226:229], v252 offset:49152
	v_add_f32_e32 v0, v155, v0
	v_cvt_pk_bf16_f32 v149, v154, v155
	v_exp_f32_e32 v157, v157
	v_add_f32_e32 v0, v156, v0
	s_waitcnt lgkmcnt(3)
	v_mfma_f32_32x32x16_bf16 v[80:95], v[6:9], v[144:147], v[80:95]
	ds_read_b128 v[2:5], v252 offset:57344
	v_exp_f32_e32 v158, v158
	v_add_f32_e32 v0, v157, v0
	v_cvt_pk_bf16_f32 v150, v156, v157
	v_exp_f32_e32 v159, v159
	v_add_f32_e32 v0, v158, v0
	v_add_f32_e32 v0, v159, v0
	v_cvt_pk_bf16_f32 v151, v158, v159
	s_waitcnt lgkmcnt(3)
	s_nop 0
	v_mfma_f32_32x32x16_bf16 v[128:143], v[10:13], v[148:151], v[128:143]
	ds_read_b128 v[6:9], v14 offset:8192
	s_add_i32 m0, s1, 0x8000
	s_nop 0
	global_load_lds_dwordx4 v198, s[74:75]
	v_add_f32_e32 v197, v197, v0
	v_exp_f32_e32 v236, v236
	v_exp_f32_e32 v237, v237
	v_exp_f32_e32 v238, v238
	s_waitcnt lgkmcnt(3)
	v_mfma_f32_32x32x16_bf16 v[112:127], v[218:221], v[148:151], v[112:127]
	ds_read_b128 v[10:13], v217 offset:8192
	v_add_f32_e32 v0, v236, v237
	v_cvt_pk_bf16_f32 v236, v236, v237
	v_exp_f32_e32 v239, v239
	v_add_f32_e32 v0, v238, v0
	s_waitcnt lgkmcnt(3)
	v_mfma_f32_32x32x16_bf16 v[96:111], v[226:229], v[148:151], v[96:111]
	ds_read_b128 v[218:221], v222 offset:8192
	v_exp_f32_e32 v240, v240
	v_add_f32_e32 v0, v239, v0
	v_cvt_pk_bf16_f32 v237, v238, v239
	v_exp_f32_e32 v241, v241
	s_waitcnt lgkmcnt(3)
	v_mfma_f32_32x32x16_bf16 v[80:95], v[2:5], v[148:151], v[80:95]
	ds_read_b128 v[226:229], v223 offset:8192
	v_add_f32_e32 v0, v240, v0
	v_exp_f32_e32 v242, v242
	v_add_f32_e32 v0, v241, v0
	v_cvt_pk_bf16_f32 v238, v240, v241
	s_waitcnt lgkmcnt(3)
	v_mfma_f32_32x32x16_bf16 v[144:159], v[6:9], v[160:163], 0
	ds_read_b128 v[2:5], v15 offset:32768
	v_exp_f32_e32 v243, v243
	v_add_f32_e32 v0, v242, v0
	v_exp_f32_e32 v244, v244
	v_add_f32_e32 v0, v243, v0
	s_waitcnt lgkmcnt(3)
	v_mfma_f32_32x32x16_bf16 v[144:159], v[10:13], v[164:167], v[144:159]
	ds_read_b128 v[6:9], v15 offset:40960
	v_cvt_pk_bf16_f32 v239, v242, v243
	v_exp_f32_e32 v245, v245
	v_add_f32_e32 v0, v244, v0
	v_exp_f32_e32 v246, v246
	s_waitcnt lgkmcnt(3)
	v_mfma_f32_32x32x16_bf16 v[144:159], v[218:221], v[168:171], v[144:159]
	ds_read_b128 v[10:13], v15 offset:49152
	v_add_f32_e32 v0, v245, v0
	v_cvt_pk_bf16_f32 v240, v244, v245
	v_exp_f32_e32 v247, v247
	v_add_f32_e32 v0, v246, v0
	s_waitcnt lgkmcnt(3)
	v_mfma_f32_32x32x16_bf16 v[144:159], v[226:229], v[172:175], v[144:159]
	ds_read_b128 v[218:221], v15 offset:57344
	v_exp_f32_e32 v248, v248
	v_add_f32_e32 v0, v247, v0
	v_cvt_pk_bf16_f32 v241, v246, v247
	v_exp_f32_e32 v249, v249
	s_waitcnt lgkmcnt(3)
	v_mfma_f32_32x32x16_bf16 v[64:79], v[2:5], v[236:239], v[64:79]
	v_xor_b32_e32 v253, 32, v15
	ds_read_b128 v[226:229], v253 offset:32768
	s_add_i32 m0, s1, 0x400
	s_nop 0
	global_load_lds_dwordx4 v208, s[74:75]
	v_add_f32_e32 v0, v248, v0
	v_exp_f32_e32 v250, v250
	v_add_f32_e32 v0, v249, v0
	v_cvt_pk_bf16_f32 v242, v248, v249
	s_waitcnt lgkmcnt(3)
	v_mfma_f32_32x32x16_bf16 v[48:63], v[6:9], v[236:239], v[48:63]
	ds_read_b128 v[2:5], v253 offset:40960
	v_exp_f32_e32 v251, v251
	v_add_f32_e32 v0, v250, v0
	v_add_f32_e32 v0, v251, v0
	v_cvt_pk_bf16_f32 v243, v250, v251
	s_waitcnt lgkmcnt(3)
	v_mfma_f32_32x32x16_bf16 v[32:47], v[10:13], v[236:239], v[32:47]
	ds_read_b128 v[6:9], v253 offset:49152
	v_add_f32_e32 v196, v196, v0
	v_exp_f32_e32 v144, v144
	v_exp_f32_e32 v145, v145
	v_exp_f32_e32 v146, v146
	s_waitcnt lgkmcnt(3)
	v_mfma_f32_32x32x16_bf16 v[16:31], v[218:221], v[236:239], v[16:31]
	ds_read_b128 v[10:13], v253 offset:57344
	v_add_f32_e32 v0, v144, v145
	v_cvt_pk_bf16_f32 v144, v144, v145
	v_exp_f32_e32 v147, v147
	v_add_f32_e32 v0, v146, v0
	s_waitcnt lgkmcnt(3)
	v_mfma_f32_32x32x16_bf16 v[64:79], v[226:229], v[240:243], v[64:79]
	ds_read_b128 v[218:221], v225 offset:8192
	v_exp_f32_e32 v148, v148
	v_add_f32_e32 v0, v147, v0
	v_cvt_pk_bf16_f32 v145, v146, v147
	v_exp_f32_e32 v149, v149
	s_waitcnt lgkmcnt(3)
	v_mfma_f32_32x32x16_bf16 v[48:63], v[2:5], v[240:243], v[48:63]
	ds_read_b128 v[226:229], v230 offset:8192
	v_add_f32_e32 v0, v148, v0
	v_exp_f32_e32 v150, v150
	v_add_f32_e32 v0, v149, v0
	v_cvt_pk_bf16_f32 v146, v148, v149
	s_waitcnt lgkmcnt(3)
	v_mfma_f32_32x32x16_bf16 v[32:47], v[6:9], v[240:243], v[32:47]
	ds_read_b128 v[2:5], v231 offset:8192
	v_exp_f32_e32 v151, v151
	v_add_f32_e32 v0, v150, v0
	v_exp_f32_e32 v152, v152
	v_add_f32_e32 v0, v151, v0
	s_waitcnt lgkmcnt(3)
	v_mfma_f32_32x32x16_bf16 v[16:31], v[10:13], v[240:243], v[16:31]
	ds_read_b128 v[6:9], v235 offset:8192
	v_cvt_pk_bf16_f32 v147, v150, v151
	v_exp_f32_e32 v153, v153
	v_add_f32_e32 v0, v152, v0
	v_exp_f32_e32 v154, v154
	s_waitcnt lgkmcnt(3)
	v_mfma_f32_32x32x16_bf16 v[236:251], v[218:221], v[176:179], 0
	v_xor_b32_e32 v252, 64, v15
	ds_read_b128 v[10:13], v252 offset:32768
	s_add_i32 m0, s1, 0x8400
	s_nop 0
	global_load_lds_dwordx4 v200, s[74:75]
	v_add_f32_e32 v0, v153, v0
	v_cvt_pk_bf16_f32 v148, v152, v153
	v_exp_f32_e32 v155, v155
	v_add_f32_e32 v0, v154, v0
	s_waitcnt lgkmcnt(3)
	v_mfma_f32_32x32x16_bf16 v[236:251], v[226:229], v[180:183], v[236:251]
	ds_read_b128 v[218:221], v252 offset:40960
	v_exp_f32_e32 v156, v156
	v_add_f32_e32 v0, v155, v0
	v_cvt_pk_bf16_f32 v149, v154, v155
	v_exp_f32_e32 v157, v157
	s_waitcnt lgkmcnt(3)
	v_mfma_f32_32x32x16_bf16 v[236:251], v[2:5], v[184:187], v[236:251]
	ds_read_b128 v[226:229], v252 offset:49152
	v_add_f32_e32 v0, v156, v0
	v_exp_f32_e32 v158, v158
	v_add_f32_e32 v0, v157, v0
	v_cvt_pk_bf16_f32 v150, v156, v157
	s_waitcnt lgkmcnt(3)
	v_mfma_f32_32x32x16_bf16 v[236:251], v[6:9], v[188:191], v[236:251]
	ds_read_b128 v[2:5], v252 offset:57344
	v_exp_f32_e32 v159, v159
	v_add_f32_e32 v0, v158, v0
	v_add_f32_e32 v0, v159, v0
	v_cvt_pk_bf16_f32 v151, v158, v159
	s_waitcnt lgkmcnt(3)
	v_mfma_f32_32x32x16_bf16 v[128:143], v[10:13], v[144:147], v[128:143]
	v_xor_b32_e32 v253, 0x60, v15
	ds_read_b128 v[6:9], v253 offset:32768
	v_add_f32_e32 v197, v197, v0
	s_waitcnt lgkmcnt(3)
	v_mfma_f32_32x32x16_bf16 v[112:127], v[218:221], v[144:147], v[112:127]
	ds_read_b128 v[10:13], v253 offset:40960
	v_exp_f32_e32 v236, v236
	v_exp_f32_e32 v237, v237
	v_exp_f32_e32 v238, v238
	v_add_f32_e32 v0, v236, v237
	v_cvt_pk_bf16_f32 v236, v236, v237
	v_exp_f32_e32 v239, v239
	v_add_f32_e32 v0, v238, v0
	s_waitcnt lgkmcnt(3)
	v_mfma_f32_32x32x16_bf16 v[96:111], v[226:229], v[144:147], v[96:111]
	ds_read_b128 v[218:221], v253 offset:49152
	v_exp_f32_e32 v240, v240
	v_add_f32_e32 v0, v239, v0
	v_cvt_pk_bf16_f32 v237, v238, v239
	v_exp_f32_e32 v241, v241
	s_waitcnt lgkmcnt(3)
	v_mfma_f32_32x32x16_bf16 v[80:95], v[2:5], v[144:147], v[80:95]
	ds_read_b128 v[226:229], v253 offset:57344
	v_add_f32_e32 v0, v240, v0
	v_exp_f32_e32 v242, v242
	v_add_f32_e32 v0, v241, v0
	v_cvt_pk_bf16_f32 v238, v240, v241
	s_waitcnt lgkmcnt(3)
	v_mfma_f32_32x32x16_bf16 v[128:143], v[6:9], v[148:151], v[128:143]
	ds_read_b128 v[2:5], v14 offset:16384
	s_add_i32 m0, s1, 0x800
	s_nop 0
	global_load_lds_dwordx4 v210, s[74:75]
	v_exp_f32_e32 v243, v243
	v_add_f32_e32 v0, v242, v0
	v_exp_f32_e32 v244, v244
	v_add_f32_e32 v0, v243, v0
	s_waitcnt lgkmcnt(3)
	v_mfma_f32_32x32x16_bf16 v[112:127], v[10:13], v[148:151], v[112:127]
	ds_read_b128 v[6:9], v217 offset:16384
	v_cvt_pk_bf16_f32 v239, v242, v243
	v_exp_f32_e32 v245, v245
	v_add_f32_e32 v0, v244, v0
	v_exp_f32_e32 v246, v246
	s_waitcnt lgkmcnt(3)
	v_mfma_f32_32x32x16_bf16 v[96:111], v[218:221], v[148:151], v[96:111]
	ds_read_b128 v[10:13], v222 offset:16384
	v_add_f32_e32 v0, v245, v0
	v_cvt_pk_bf16_f32 v240, v244, v245
	v_exp_f32_e32 v247, v247
	v_add_f32_e32 v0, v246, v0
	s_waitcnt lgkmcnt(3)
	v_mfma_f32_32x32x16_bf16 v[80:95], v[226:229], v[148:151], v[80:95]
	ds_read_b128 v[218:221], v223 offset:16384
	v_exp_f32_e32 v248, v248
	v_add_f32_e32 v0, v247, v0
	v_cvt_pk_bf16_f32 v241, v246, v247
	v_exp_f32_e32 v249, v249
	s_waitcnt lgkmcnt(3)
	v_mfma_f32_32x32x16_bf16 v[144:159], v[2:5], v[160:163], 0
	v_xor_b32_e32 v252, 64, v15
	ds_read_b128 v[226:229], v252 offset:32768
	v_add_f32_e32 v0, v248, v0
	v_exp_f32_e32 v250, v250
	v_add_f32_e32 v0, v249, v0
	v_cvt_pk_bf16_f32 v242, v248, v249
	s_waitcnt lgkmcnt(3)
	v_mfma_f32_32x32x16_bf16 v[144:159], v[6:9], v[164:167], v[144:159]
	ds_read_b128 v[2:5], v252 offset:40960
	v_exp_f32_e32 v251, v251
	v_add_f32_e32 v0, v250, v0
	v_add_f32_e32 v0, v251, v0
	v_cvt_pk_bf16_f32 v243, v250, v251
	s_waitcnt lgkmcnt(3)
	v_mfma_f32_32x32x16_bf16 v[144:159], v[10:13], v[168:171], v[144:159]
	ds_read_b128 v[6:9], v252 offset:49152
	v_add_f32_e32 v196, v196, v0
	s_waitcnt lgkmcnt(3)
	v_mfma_f32_32x32x16_bf16 v[144:159], v[218:221], v[172:175], v[144:159]
	ds_read_b128 v[10:13], v252 offset:57344
	s_waitcnt lgkmcnt(3)
	v_mfma_f32_32x32x16_bf16 v[64:79], v[226:229], v[236:239], v[64:79]
	v_xor_b32_e32 v253, 0x60, v15
	ds_read_b128 v[218:221], v253 offset:32768
	s_add_i32 m0, s1, 0x8800
	s_nop 0
	global_load_lds_dwordx4 v202, s[74:75]
	s_waitcnt lgkmcnt(3)
	v_mfma_f32_32x32x16_bf16 v[48:63], v[2:5], v[236:239], v[48:63]
	ds_read_b128 v[226:229], v253 offset:40960
	s_nop 0
	v_exp_f32_e32 v144, v144
	v_exp_f32_e32 v145, v145
	v_exp_f32_e32 v146, v146
	v_add_f32_e32 v0, v144, v145
	v_cvt_pk_bf16_f32 v144, v144, v145
	v_exp_f32_e32 v147, v147
	v_add_f32_e32 v0, v146, v0
	v_exp_f32_e32 v148, v148
	s_waitcnt lgkmcnt(3)
	v_mfma_f32_32x32x16_bf16 v[32:47], v[6:9], v[236:239], v[32:47]
	ds_read_b128 v[2:5], v253 offset:49152
	v_add_f32_e32 v0, v147, v0
	v_cvt_pk_bf16_f32 v145, v146, v147
	v_exp_f32_e32 v149, v149
	v_add_f32_e32 v0, v148, v0
	s_waitcnt lgkmcnt(3)
	v_mfma_f32_32x32x16_bf16 v[16:31], v[10:13], v[236:239], v[16:31]
	ds_read_b128 v[6:9], v253 offset:57344
	v_exp_f32_e32 v150, v150
	v_add_f32_e32 v0, v149, v0
	v_cvt_pk_bf16_f32 v146, v148, v149
	v_exp_f32_e32 v151, v151
	s_waitcnt lgkmcnt(3)
	v_mfma_f32_32x32x16_bf16 v[64:79], v[218:221], v[240:243], v[64:79]
	ds_read_b128 v[10:13], v225 offset:16384
	v_add_f32_e32 v0, v150, v0
	v_exp_f32_e32 v152, v152
	v_add_f32_e32 v0, v151, v0
	v_cvt_pk_bf16_f32 v147, v150, v151
	s_waitcnt lgkmcnt(3)
	v_mfma_f32_32x32x16_bf16 v[48:63], v[226:229], v[240:243], v[48:63]
	ds_read_b128 v[218:221], v230 offset:16384
	v_exp_f32_e32 v153, v153
	v_add_f32_e32 v0, v152, v0
	v_exp_f32_e32 v154, v154
	v_add_f32_e32 v0, v153, v0
	s_waitcnt lgkmcnt(3)
	v_mfma_f32_32x32x16_bf16 v[32:47], v[2:5], v[240:243], v[32:47]
	ds_read_b128 v[226:229], v231 offset:16384
	v_cvt_pk_bf16_f32 v148, v152, v153
	v_exp_f32_e32 v155, v155
	v_add_f32_e32 v0, v154, v0
	v_exp_f32_e32 v156, v156
	s_waitcnt lgkmcnt(3)
	v_mfma_f32_32x32x16_bf16 v[16:31], v[6:9], v[240:243], v[16:31]
	ds_read_b128 v[2:5], v235 offset:16384
	v_add_f32_e32 v0, v155, v0
	v_cvt_pk_bf16_f32 v149, v154, v155
	v_exp_f32_e32 v157, v157
	v_add_f32_e32 v0, v156, v0
	s_waitcnt lgkmcnt(3)
	v_mfma_f32_32x32x16_bf16 v[236:251], v[10:13], v[176:179], 0
	v_xor_b32_e32 v252, 0x80, v15
	ds_read_b128 v[6:9], v252 offset:32768
	s_add_i32 m0, s1, 0xc00
	s_nop 0
	global_load_lds_dwordx4 v212, s[74:75]
	v_exp_f32_e32 v158, v158
	v_add_f32_e32 v0, v157, v0
	v_cvt_pk_bf16_f32 v150, v156, v157
	v_exp_f32_e32 v159, v159
	s_waitcnt lgkmcnt(3)
	v_mfma_f32_32x32x16_bf16 v[236:251], v[218:221], v[180:183], v[236:251]
	ds_read_b128 v[10:13], v252 offset:40960
	v_add_f32_e32 v0, v158, v0
	v_add_f32_e32 v0, v159, v0
	v_cvt_pk_bf16_f32 v151, v158, v159
	v_add_f32_e32 v197, v197, v0
	s_waitcnt lgkmcnt(3)
	v_mfma_f32_32x32x16_bf16 v[236:251], v[226:229], v[184:187], v[236:251]
	ds_read_b128 v[218:221], v252 offset:49152
	s_waitcnt lgkmcnt(3)
	v_mfma_f32_32x32x16_bf16 v[236:251], v[2:5], v[188:191], v[236:251]
	ds_read_b128 v[226:229], v252 offset:57344
	s_waitcnt lgkmcnt(3)
	v_mfma_f32_32x32x16_bf16 v[128:143], v[6:9], v[144:147], v[128:143]
	v_xor_b32_e32 v253, 0xa0, v15
	ds_read_b128 v[2:5], v253 offset:32768
	s_waitcnt lgkmcnt(3)
	v_mfma_f32_32x32x16_bf16 v[112:127], v[10:13], v[144:147], v[112:127]
	ds_read_b128 v[6:9], v253 offset:40960
	s_nop 3
	v_exp_f32_e32 v236, v236
	v_exp_f32_e32 v237, v237
	v_exp_f32_e32 v238, v238
	v_add_f32_e32 v0, v236, v237
	v_cvt_pk_bf16_f32 v236, v236, v237
	v_exp_f32_e32 v239, v239
	v_add_f32_e32 v0, v238, v0
	v_exp_f32_e32 v240, v240
	s_waitcnt lgkmcnt(3)
	v_mfma_f32_32x32x16_bf16 v[96:111], v[218:221], v[144:147], v[96:111]
	ds_read_b128 v[10:13], v253 offset:49152
	v_add_f32_e32 v0, v239, v0
	v_cvt_pk_bf16_f32 v237, v238, v239
	v_exp_f32_e32 v241, v241
	v_add_f32_e32 v0, v240, v0
	s_waitcnt lgkmcnt(3)
	v_mfma_f32_32x32x16_bf16 v[80:95], v[226:229], v[144:147], v[80:95]
	ds_read_b128 v[218:221], v253 offset:57344
	v_exp_f32_e32 v242, v242
	v_add_f32_e32 v0, v241, v0
	v_cvt_pk_bf16_f32 v238, v240, v241
	v_exp_f32_e32 v243, v243
	s_waitcnt lgkmcnt(3)
	v_mfma_f32_32x32x16_bf16 v[128:143], v[2:5], v[148:151], v[128:143]
	ds_read_b128 v[226:229], v14 offset:24576
	s_add_i32 m0, s1, 0x8c00
	s_nop 0
	global_load_lds_dwordx4 v204, s[74:75]
	v_add_f32_e32 v0, v242, v0
	v_exp_f32_e32 v244, v244
	v_add_f32_e32 v0, v243, v0
	v_cvt_pk_bf16_f32 v239, v242, v243
	s_waitcnt lgkmcnt(3)
	v_mfma_f32_32x32x16_bf16 v[112:127], v[6:9], v[148:151], v[112:127]
	ds_read_b128 v[2:5], v217 offset:24576
	v_exp_f32_e32 v245, v245
	v_add_f32_e32 v0, v244, v0
	v_exp_f32_e32 v246, v246
	v_add_f32_e32 v0, v245, v0
	s_waitcnt lgkmcnt(3)
	v_mfma_f32_32x32x16_bf16 v[96:111], v[10:13], v[148:151], v[96:111]
	ds_read_b128 v[6:9], v222 offset:24576
	v_cvt_pk_bf16_f32 v240, v244, v245
	v_exp_f32_e32 v247, v247
	v_add_f32_e32 v0, v246, v0
	v_exp_f32_e32 v248, v248
	s_waitcnt lgkmcnt(3)
	v_mfma_f32_32x32x16_bf16 v[80:95], v[218:221], v[148:151], v[80:95]
	ds_read_b128 v[10:13], v223 offset:24576
	v_add_f32_e32 v0, v247, v0
	v_cvt_pk_bf16_f32 v241, v246, v247
	v_exp_f32_e32 v249, v249
	v_add_f32_e32 v0, v248, v0
	s_waitcnt lgkmcnt(3)
	v_mfma_f32_32x32x16_bf16 v[144:159], v[226:229], v[160:163], 0
	v_xor_b32_e32 v252, 0x80, v15
	ds_read_b128 v[218:221], v252 offset:32768
	v_exp_f32_e32 v250, v250
	v_add_f32_e32 v0, v249, v0
	v_cvt_pk_bf16_f32 v242, v248, v249
	v_exp_f32_e32 v251, v251
	s_waitcnt lgkmcnt(3)
	v_mfma_f32_32x32x16_bf16 v[144:159], v[2:5], v[164:167], v[144:159]
	ds_read_b128 v[226:229], v252 offset:40960
	v_add_f32_e32 v0, v250, v0
	v_add_f32_e32 v0, v251, v0
	v_cvt_pk_bf16_f32 v243, v250, v251
	v_add_f32_e32 v196, v196, v0
	s_waitcnt lgkmcnt(3)
	v_mfma_f32_32x32x16_bf16 v[144:159], v[6:9], v[168:171], v[144:159]
	ds_read_b128 v[2:5], v252 offset:49152
	s_waitcnt lgkmcnt(3)
	v_mfma_f32_32x32x16_bf16 v[144:159], v[10:13], v[172:175], v[144:159]
	ds_read_b128 v[6:9], v252 offset:57344
	s_waitcnt lgkmcnt(3)
	v_mfma_f32_32x32x16_bf16 v[64:79], v[218:221], v[236:239], v[64:79]
	v_xor_b32_e32 v253, 0xa0, v15
	ds_read_b128 v[10:13], v253 offset:32768
	s_waitcnt lgkmcnt(3)
	v_mfma_f32_32x32x16_bf16 v[48:63], v[226:229], v[236:239], v[48:63]
	ds_read_b128 v[218:221], v253 offset:40960
	s_nop 3
	v_exp_f32_e32 v144, v144
	v_exp_f32_e32 v145, v145
	v_exp_f32_e32 v146, v146
	v_add_f32_e32 v0, v144, v145
	v_cvt_pk_bf16_f32 v144, v144, v145
	v_exp_f32_e32 v147, v147
	v_add_f32_e32 v0, v146, v0
	v_exp_f32_e32 v148, v148
	s_waitcnt lgkmcnt(3)
	v_mfma_f32_32x32x16_bf16 v[32:47], v[2:5], v[236:239], v[32:47]
	ds_read_b128 v[226:229], v253 offset:49152
	v_add_f32_e32 v0, v147, v0
	v_cvt_pk_bf16_f32 v145, v146, v147
	v_exp_f32_e32 v149, v149
	v_add_f32_e32 v0, v148, v0
	s_waitcnt lgkmcnt(3)
	v_mfma_f32_32x32x16_bf16 v[16:31], v[6:9], v[236:239], v[16:31]
	ds_read_b128 v[2:5], v253 offset:57344
	v_exp_f32_e32 v150, v150
	v_add_f32_e32 v0, v149, v0
	v_cvt_pk_bf16_f32 v146, v148, v149
	v_exp_f32_e32 v151, v151
	s_waitcnt lgkmcnt(3)
	v_mfma_f32_32x32x16_bf16 v[64:79], v[10:13], v[240:243], v[64:79]
	ds_read_b128 v[6:9], v225 offset:24576
	v_add_f32_e32 v0, v150, v0
	v_exp_f32_e32 v152, v152
	v_add_f32_e32 v0, v151, v0
	v_cvt_pk_bf16_f32 v147, v150, v151
	s_waitcnt lgkmcnt(3)
	v_mfma_f32_32x32x16_bf16 v[48:63], v[218:221], v[240:243], v[48:63]
	ds_read_b128 v[10:13], v230 offset:24576
	v_exp_f32_e32 v153, v153
	v_add_f32_e32 v0, v152, v0
	v_exp_f32_e32 v154, v154
	v_add_f32_e32 v0, v153, v0
	s_waitcnt lgkmcnt(3)
	v_mfma_f32_32x32x16_bf16 v[32:47], v[226:229], v[240:243], v[32:47]
	ds_read_b128 v[218:221], v231 offset:24576
	v_cvt_pk_bf16_f32 v148, v152, v153
	v_exp_f32_e32 v155, v155
	v_add_f32_e32 v0, v154, v0
	v_exp_f32_e32 v156, v156
	s_waitcnt lgkmcnt(3)
	v_mfma_f32_32x32x16_bf16 v[16:31], v[2:5], v[240:243], v[16:31]
	ds_read_b128 v[226:229], v235 offset:24576
	v_add_f32_e32 v0, v155, v0
	v_cvt_pk_bf16_f32 v149, v154, v155
	v_exp_f32_e32 v157, v157
	v_add_f32_e32 v0, v156, v0
	s_waitcnt lgkmcnt(3)
	v_mfma_f32_32x32x16_bf16 v[236:251], v[6:9], v[176:179], 0
	v_xor_b32_e32 v252, 0xc0, v15
	ds_read_b128 v[2:5], v252 offset:32768
	v_exp_f32_e32 v158, v158
	v_add_f32_e32 v0, v157, v0
	v_cvt_pk_bf16_f32 v150, v156, v157
	v_exp_f32_e32 v159, v159
	s_waitcnt lgkmcnt(3)
	v_mfma_f32_32x32x16_bf16 v[236:251], v[10:13], v[180:183], v[236:251]
	ds_read_b128 v[6:9], v252 offset:40960
	v_add_f32_e32 v0, v158, v0
	v_add_f32_e32 v0, v159, v0
	v_cvt_pk_bf16_f32 v151, v158, v159
	v_add_f32_e32 v197, v197, v0
	s_waitcnt lgkmcnt(3)
	v_mfma_f32_32x32x16_bf16 v[236:251], v[218:221], v[184:187], v[236:251]
	ds_read_b128 v[10:13], v252 offset:49152
	s_waitcnt lgkmcnt(3)
	v_mfma_f32_32x32x16_bf16 v[236:251], v[226:229], v[188:191], v[236:251]
	ds_read_b128 v[218:221], v252 offset:57344
	s_waitcnt lgkmcnt(3)
	v_mfma_f32_32x32x16_bf16 v[128:143], v[2:5], v[144:147], v[128:143]
	v_xor_b32_e32 v253, 0xe0, v15
	ds_read_b128 v[226:229], v253 offset:32768
	s_waitcnt lgkmcnt(3)
	v_mfma_f32_32x32x16_bf16 v[112:127], v[6:9], v[144:147], v[112:127]
	ds_read_b128 v[2:5], v253 offset:40960
	s_nop 3
	v_exp_f32_e32 v236, v236
	v_exp_f32_e32 v237, v237
	v_exp_f32_e32 v238, v238
	v_add_f32_e32 v0, v236, v237
	v_cvt_pk_bf16_f32 v236, v236, v237
	v_exp_f32_e32 v239, v239
	v_add_f32_e32 v0, v238, v0
	v_exp_f32_e32 v240, v240
	s_waitcnt lgkmcnt(3)
	v_mfma_f32_32x32x16_bf16 v[96:111], v[10:13], v[144:147], v[96:111]
	ds_read_b128 v[6:9], v253 offset:49152
	v_add_f32_e32 v0, v239, v0
	v_cvt_pk_bf16_f32 v237, v238, v239
	v_exp_f32_e32 v241, v241
	v_add_f32_e32 v0, v240, v0
	s_waitcnt lgkmcnt(3)
	v_mfma_f32_32x32x16_bf16 v[80:95], v[218:221], v[144:147], v[80:95]
	ds_read_b128 v[10:13], v253 offset:57344
	v_exp_f32_e32 v242, v242
	v_add_f32_e32 v0, v241, v0
	v_cvt_pk_bf16_f32 v238, v240, v241
	v_exp_f32_e32 v243, v243
	s_waitcnt lgkmcnt(3)
	v_mfma_f32_32x32x16_bf16 v[128:143], v[226:229], v[148:151], v[128:143]
	v_xor_b32_e32 v252, 0xc0, v15
	ds_read_b128 v[218:221], v252 offset:32768
	v_add_f32_e32 v0, v242, v0
	v_exp_f32_e32 v244, v244
	v_add_f32_e32 v0, v243, v0
	v_cvt_pk_bf16_f32 v239, v242, v243
	s_waitcnt lgkmcnt(3)
	v_mfma_f32_32x32x16_bf16 v[112:127], v[2:5], v[148:151], v[112:127]
	ds_read_b128 v[226:229], v252 offset:40960
	v_exp_f32_e32 v245, v245
	v_add_f32_e32 v0, v244, v0
	v_exp_f32_e32 v246, v246
	v_add_f32_e32 v0, v245, v0
	s_waitcnt lgkmcnt(3)
	v_mfma_f32_32x32x16_bf16 v[96:111], v[6:9], v[148:151], v[96:111]
	ds_read_b128 v[2:5], v252 offset:49152
	v_cvt_pk_bf16_f32 v240, v244, v245
	v_exp_f32_e32 v247, v247
	v_add_f32_e32 v0, v246, v0
	v_exp_f32_e32 v248, v248
	s_waitcnt lgkmcnt(3)
	v_mfma_f32_32x32x16_bf16 v[80:95], v[10:13], v[148:151], v[80:95]
	ds_read_b128 v[6:9], v252 offset:57344
	v_add_f32_e32 v0, v247, v0
	v_cvt_pk_bf16_f32 v241, v246, v247
	v_exp_f32_e32 v249, v249
	v_add_f32_e32 v0, v248, v0
	s_waitcnt lgkmcnt(3)
	v_mfma_f32_32x32x16_bf16 v[64:79], v[218:221], v[236:239], v[64:79]
	v_xor_b32_e32 v253, 0xe0, v15
	ds_read_b128 v[10:13], v253 offset:32768
	v_exp_f32_e32 v250, v250
	v_add_f32_e32 v0, v249, v0
	v_cvt_pk_bf16_f32 v242, v248, v249
	v_exp_f32_e32 v251, v251
	s_waitcnt lgkmcnt(3)
	v_mfma_f32_32x32x16_bf16 v[48:63], v[226:229], v[236:239], v[48:63]
	ds_read_b128 v[218:221], v253 offset:40960
	v_add_f32_e32 v0, v250, v0
	v_add_f32_e32 v0, v251, v0
	v_cvt_pk_bf16_f32 v243, v250, v251
	v_add_f32_e32 v196, v196, v0
	s_waitcnt lgkmcnt(3)
	v_mfma_f32_32x32x16_bf16 v[32:47], v[2:5], v[236:239], v[32:47]
	ds_read_b128 v[226:229], v253 offset:49152
	s_waitcnt lgkmcnt(3)
	v_mfma_f32_32x32x16_bf16 v[16:31], v[6:9], v[236:239], v[16:31]
	ds_read_b128 v[2:5], v253 offset:57344
	s_waitcnt lgkmcnt(3)
	v_mfma_f32_32x32x16_bf16 v[64:79], v[10:13], v[240:243], v[64:79]
	s_waitcnt lgkmcnt(2)
	v_mfma_f32_32x32x16_bf16 v[48:63], v[218:221], v[240:243], v[48:63]
	s_waitcnt lgkmcnt(1)
	v_mfma_f32_32x32x16_bf16 v[32:47], v[226:229], v[240:243], v[32:47]
	s_waitcnt lgkmcnt(0)
	v_mfma_f32_32x32x16_bf16 v[16:31], v[2:5], v[240:243], v[16:31]

.LBB0_421:
	s_waitcnt vmcnt(0)
	s_add_i32 s1, s29, s36
	s_and_b32 s0, s36, 1
	s_add_i32 s1, s1, 1
	s_cmp_ge_u32 s1, s30
	s_waitcnt lgkmcnt(0)
	s_barrier
	s_add_i32 s4, s35, 0xffffff81
	s_cmp_gt_u32 s4, s34
	s_cbranch_scc0 .Ldiff_dispatch
	s_add_i32 s1, s29, s36
	s_add_i32 s1, s1, 1
	s_cmp_ge_u32 s1, s30
	s_cbranch_scc1 .LBB0_420
	s_lshl_b32 s1, s0, 16
	s_xor_b32 s1, s1, 0x10000
	s_add_i32 s1, s41, s1
	v_lshl_add_u64 v[2:3], s[74:75], 0, v[206:207]
	s_mov_b32 m0, s1
	s_nop 0
	global_load_lds_dwordx4 v[2:3], off
	v_lshl_add_u64 v[2:3], s[74:75], 0, v[198:199]
	s_add_i32 m0, s1, 0x8000
	s_nop 0
	global_load_lds_dwordx4 v[2:3], off
	v_lshl_add_u64 v[2:3], s[74:75], 0, v[208:209]
	s_add_i32 m0, s1, 0x400
	s_nop 0
	global_load_lds_dwordx4 v[2:3], off
	v_lshl_add_u64 v[2:3], s[74:75], 0, v[200:201]
	s_add_i32 m0, s1, 0x8400
	s_nop 0
	global_load_lds_dwordx4 v[2:3], off
	v_lshl_add_u64 v[2:3], s[74:75], 0, v[210:211]
	s_add_i32 m0, s1, 0x800
	s_nop 0
	global_load_lds_dwordx4 v[2:3], off
	v_lshl_add_u64 v[2:3], s[74:75], 0, v[202:203]
	s_add_i32 m0, s1, 0x8800
	s_nop 0
	global_load_lds_dwordx4 v[2:3], off
	v_lshl_add_u64 v[2:3], s[74:75], 0, v[212:213]
	s_add_i32 m0, s1, 0xc00
	s_nop 0
	global_load_lds_dwordx4 v[2:3], off
	v_lshl_add_u64 v[2:3], s[74:75], 0, v[204:205]
	s_add_i32 m0, s1, 0x8c00
	s_nop 0
	global_load_lds_dwordx4 v[2:3], off
	s_branch .LBB0_420
.Ldiff_dispatch:
	s_cmp_gt_u32 s35, s31
	s_cbranch_scc0 .Ldiff_fast0
	s_branch .Ldiff_mask0

.LBB0_441:
	s_waitcnt vmcnt(0)
	v_cmp_eq_u32_e32 vcc, 0, v235
	s_and_b64 s[4:5], s[14:15], vcc
	s_waitcnt lgkmcnt(0)
	s_barrier
	s_and_saveexec_b64 s[0:1], s[4:5]
	s_cbranch_execz .LBB0_443
	s_cmp_lg_u32 s98, 0
	s_cbranch_scc1 .Lnowb_diff
	buffer_wbl2 sc1
	s_waitcnt vmcnt(0)
.Lnowb_diff:
	s_waitcnt vmcnt(0)
	s_or_b64 s[82:83], s[82:83], exec
